# blocked H + P0: gain hoist + every wave runs the x pass then the weight work (8G waves each) instead of the 2/6 wave-role split
# speedup vs baseline: 1.0061x; 1.0015x over previous
; #define GAS __attribute__((address_space(1)))
; #define LAS __attribute__((address_space(3)))
; __device__ __forceinline__ void p0_prologue(Frame& F) {
;     LAS float* scr = (LAS float*)(F.lds + RING_OFF + F.wave * 16384);
;     if (F.wave < P0_WW) {
;     const int gw = F.vcu * P0_WW + F.wave, NGW = F.G * P0_WW;
;     const int gt = gw * 64 + F.lane, NGT = NGW * 64;
;     ...
;     const int gw = F.vcu * (NWAVES - P0_WW) + (F.wave - P0_WW), NGW = F.G * (NWAVES - P0_WW);
;     for (int m = gw; m < M; m += 4 * NGW) {
;         f32x4 v[4][4];
; #pragma unroll
;         for (int q = 0; q < 4; ++q) { const int mm = m + q * NGW; if (mm < M) { const float* xrow = mm < ROWS_P ? F.xp + (size_t)mm * D : F.xs + (size_t)(mm - ROWS_P) * D; const GAS f32x4* xr = (const GAS f32x4*)xrow + 2 * F.lane;
.LBB0_13:
	s_or_b64 exec, exec, s[4:5]
	s_add_u32 s78, s62, 0x900000
	s_addc_u32 s79, s63, 0
	s_add_u32 s64, s62, 0x1300000
	s_addc_u32 s65, s63, 0
	s_add_u32 s18, s62, 0x102000
	s_addc_u32 s19, s63, 0
	s_add_u32 s80, s62, 0x110000
	s_addc_u32 s81, s63, 0
	s_add_u32 s16, s62, 0x600000
	s_addc_u32 s17, s63, 0
	s_add_u32 s74, s62, 0xb00000
	s_addc_u32 s75, s63, 0
	s_add_u32 s66, s62, 0x2000000
	s_addc_u32 s67, s63, 0
	s_add_u32 s20, s62, 0x100000
	s_addc_u32 s21, s63, 0
	s_lshr_b32 s87, s88, 6
	s_cmp_gt_i32 s69, -1
	s_cselect_b64 s[0:1], -1, 0
	s_abs_i32 s33, s69
	s_cmp_lt_i32 s68, 1
	s_cselect_b64 s[4:5], -1, 0
	s_cmp_lg_u32 s69, 0
	s_cselect_b64 s[6:7], -1, 0
	s_and_b64 s[4:5], s[4:5], s[6:7]
	v_writelane_b32 v254, s0, 2
	s_andn2_b64 vcc, exec, s[4:5]
	v_and_b32_e32 v1, 63, v208
	v_writelane_b32 v254, s1, 3
	s_cbranch_vccnz .LBB0_235
	s_cmpk_gt_u32 s88, 0x7f
	s_mov_b64 s[4:5], -1
	s_nop 0
	s_lshl_b32 s38, s43, 3
	s_add_i32 s0, s87, s38
	s_add_i32 s0, s0, 0
	s_cmp_gt_i32 s0, 0xbfff
	s_cbranch_scc1 .LBB0_38
	v_mbcnt_lo_u32_b32 v2, -1, 0
	v_mbcnt_hi_u32_b32 v2, -1, v2
	v_and_b32_e32 v3, 64, v2
	v_add_u32_e32 v3, 64, v3
	v_xor_b32_e32 v4, 1, v2
	v_cmp_lt_i32_e32 vcc, v4, v3
	v_mov_b32_e32 v67, 0
	v_lshlrev_b32_e32 v66, 5, v1
	v_cndmask_b32_e32 v4, v2, v4, vcc
	v_lshlrev_b32_e32 v72, 2, v4
	v_xor_b32_e32 v4, 2, v2
	v_cmp_lt_i32_e32 vcc, v4, v3
	s_lshl_b32 s1, s42, 4
	s_lshl_b32 s0, s42, 3
	v_cndmask_b32_e32 v4, v2, v4, vcc
	v_lshlrev_b32_e32 v73, 2, v4
	v_xor_b32_e32 v4, 4, v2
	v_cmp_lt_i32_e32 vcc, v4, v3
	v_lshl_add_u64 v[68:69], s[48:49], 0, v[66:67]
	global_load_dwordx4 v[90:93], v[68:69], off
	global_load_dwordx4 v[94:97], v[68:69], off offset:16
	global_load_dwordx4 v[98:101], v[68:69], off offset:2048
	global_load_dwordx4 v[102:105], v[68:69], off offset:2064
	v_lshlrev_b32_e32 v66, 4, v1
	v_cndmask_b32_e32 v4, v2, v4, vcc
	v_lshlrev_b32_e32 v74, 2, v4
	v_xor_b32_e32 v4, 8, v2
	v_cmp_lt_i32_e32 vcc, v4, v3
	s_add_i32 s39, s87, s1
	s_mul_i32 s1, s42, 24
	v_cndmask_b32_e32 v4, v2, v4, vcc
	v_lshlrev_b32_e32 v75, 2, v4
	v_xor_b32_e32 v4, 16, v2
	v_cmp_lt_i32_e32 vcc, v4, v3
	v_cmp_eq_u32_e64 s[4:5], 0, v1
	v_lshl_add_u64 v[70:71], s[66:67], 0, v[66:67]
	v_cndmask_b32_e32 v4, v2, v4, vcc
	v_lshlrev_b32_e32 v76, 2, v4
	v_xor_b32_e32 v4, 32, v2
	v_cmp_lt_i32_e32 vcc, v4, v3
	s_lshl_b32 s40, s42, 5
	s_add_i32 s41, s87, s1
	v_cndmask_b32_e32 v2, v2, v4, vcc
	v_lshlrev_b32_e32 v77, 2, v2
	v_lshlrev_b32_e32 v2, 1, v1
	s_add_i32 s69, s87, s0
	v_lshlrev_b32_e32 v78, 4, v2
	v_mov_b32_e32 v79, 0x358637bd
	s_mov_b32 s72, s87
	s_branch .LBB0_19

; #define GAS __attribute__((address_space(1)))
; __device__ __forceinline__ void p0_prologue(Frame& F) {
;     ...
;     for (int m = gw; m < M; m += 4 * NGW) {
;         f32x4 v[4][4];
; #pragma unroll
;         for (int q = 0; q < 4; ++q) { const int mm = m + q * NGW; if (mm < M) { const float* xrow = mm < ROWS_P ? F.xp + (size_t)mm * D : F.xs + (size_t)(mm - ROWS_P) * D; const GAS f32x4* xr = (const GAS f32x4*)xrow + 2 * F.lane;
; #pragma unroll
;             for (int j = 0; j < 2; ++j) { v[q][2 * j] = __builtin_nontemporal_load(xr + 128 * j); v[q][2 * j + 1] = __builtin_nontemporal_load(xr + 128 * j + 1); } } else {
; #pragma unroll
;             for (int j = 0; j < 4; ++j) v[q][j] = (f32x4){0.f, 0.f, 0.f, 0.f}; } }
.LBB0_18:
	s_add_i32 s72, s72, s40
	s_add_i32 s0, s38, s72
	s_add_i32 s39, s39, s40
	s_add_i32 s41, s41, s40
	s_add_i32 s0, s0, 0
	s_add_i32 s69, s69, s40
	s_cmp_lt_i32 s0, 0xc000
	s_cbranch_scc0 .LBB0_38
.LBB0_19:
	s_add_i32 s0, s38, s72
	s_add_i32 s34, s0, 0
	s_add_i32 s0, s0, 0xffff8000
	s_ashr_i32 s35, s34, 31
	s_cmp_lt_i32 s34, 0x8000
	s_cselect_b32 s7, s35, 0
	s_cselect_b32 s6, s34, s0
	s_cselect_b32 s0, s45, s47
	s_cselect_b32 s1, s44, s46
	s_lshl_b64 s[6:7], s[6:7], 12
	s_add_u32 s6, s1, s6
	s_addc_u32 s7, s0, s7
	global_load_dwordx4 v[58:61], v78, s[6:7] offset:16 nt
	global_load_dwordx4 v[62:65], v78, s[6:7] nt
	global_load_dwordx4 v[50:53], v78, s[6:7] offset:2064 nt
	global_load_dwordx4 v[54:57], v78, s[6:7] offset:2048 nt
	s_add_i32 s6, s38, s69
	s_add_i32 s26, s6, 0
	s_cmp_lt_i32 s26, 0xc000
	s_cselect_b64 s[30:31], -1, 0
	s_cmp_gt_i32 s26, 0xbfff
	v_mov_b32_e32 v30, 0
	v_mov_b32_e32 v31, 0
	v_mov_b32_e32 v32, 0
	v_mov_b32_e32 v33, 0
	v_mov_b32_e32 v38, 0
	v_mov_b32_e32 v39, 0
	v_mov_b32_e32 v40, 0
	v_mov_b32_e32 v41, 0
	v_mov_b32_e32 v42, 0
	v_mov_b32_e32 v43, 0
	v_mov_b32_e32 v44, 0
	v_mov_b32_e32 v45, 0
	v_mov_b32_e32 v46, 0
	v_mov_b32_e32 v47, 0
	v_mov_b32_e32 v48, 0
	v_mov_b32_e32 v49, 0
	s_cbranch_scc1 .LBB0_21
	s_ashr_i32 s0, s26, 31
	s_add_i32 s6, s6, 0xffff8000
	s_cmp_lt_i32 s26, 0x8000
	s_cselect_b32 s7, s0, 0
	s_cselect_b32 s6, s26, s6
	s_cselect_b32 s0, s45, s47
	s_cselect_b32 s1, s44, s46
	s_lshl_b64 s[6:7], s[6:7], 12
	s_add_u32 s6, s1, s6
	s_addc_u32 s7, s0, s7
	global_load_dwordx4 v[42:45], v78, s[6:7] offset:16 nt
	global_load_dwordx4 v[46:49], v78, s[6:7] nt
	global_load_dwordx4 v[30:33], v78, s[6:7] offset:2064 nt
	global_load_dwordx4 v[38:41], v78, s[6:7] offset:2048 nt
.LBB0_21:
	s_add_i32 s6, s38, s39
	s_add_i32 s22, s6, 0
	s_cmp_lt_i32 s22, 0xc000
	v_mov_b32_e32 v2, 0
	s_cselect_b64 s[28:29], -1, 0
	s_cmp_gt_i32 s22, 0xbfff
	v_mov_b32_e32 v18, 0
	v_mov_b32_e32 v19, 0
	v_mov_b32_e32 v20, 0
	v_mov_b32_e32 v21, 0
	v_mov_b32_e32 v22, 0
	v_mov_b32_e32 v23, 0
	v_mov_b32_e32 v24, 0
	v_mov_b32_e32 v25, 0
	v_mov_b32_e32 v26, 0
	v_mov_b32_e32 v27, 0
	v_mov_b32_e32 v28, 0
	v_mov_b32_e32 v29, 0
	v_mov_b32_e32 v34, 0
	v_mov_b32_e32 v35, 0
	v_mov_b32_e32 v36, 0
	v_mov_b32_e32 v37, 0
	s_cbranch_scc1 .LBB0_23
	s_ashr_i32 s0, s22, 31
	s_add_i32 s6, s6, 0xffff8000
	s_cmp_lt_i32 s22, 0x8000
	s_cselect_b32 s7, s0, 0
	s_cselect_b32 s6, s22, s6
	s_cselect_b32 s0, s45, s47
	s_cselect_b32 s1, s44, s46
	s_lshl_b64 s[6:7], s[6:7], 12
	s_add_u32 s6, s1, s6
	s_addc_u32 s7, s0, s7
	global_load_dwordx4 v[26:29], v78, s[6:7] offset:16 nt
	global_load_dwordx4 v[34:37], v78, s[6:7] nt
	global_load_dwordx4 v[18:21], v78, s[6:7] offset:2064 nt
	global_load_dwordx4 v[22:25], v78, s[6:7] offset:2048 nt
.LBB0_23:
	s_add_i32 s7, s38, s41
	s_add_i32 s6, s7, 0
	s_cmp_lt_i32 s6, 0xc000
	s_cselect_b64 s[24:25], -1, 0
	s_cmp_gt_i32 s6, 0xbfff
	v_mov_b32_e32 v3, 0
	v_mov_b32_e32 v4, 0
	v_mov_b32_e32 v5, 0
	v_mov_b32_e32 v6, 0
	v_mov_b32_e32 v7, 0
	v_mov_b32_e32 v8, 0
	v_mov_b32_e32 v9, 0
	v_mov_b32_e32 v10, 0
	v_mov_b32_e32 v11, 0
	v_mov_b32_e32 v12, 0
	v_mov_b32_e32 v13, 0
	v_mov_b32_e32 v14, 0
	v_mov_b32_e32 v15, 0
	v_mov_b32_e32 v16, 0
	v_mov_b32_e32 v17, 0
	s_cbranch_scc1 .LBB0_25
	s_ashr_i32 s0, s6, 31
	s_add_i32 s7, s7, 0xffff8000
	s_cmp_lt_i32 s6, 0x8000
	s_cselect_b32 s37, s0, 0
	s_cselect_b32 s36, s6, s7
	s_cselect_b32 s0, s45, s47
	s_cselect_b32 s1, s44, s46
	s_lshl_b64 s[36:37], s[36:37], 12
	s_add_u32 s36, s1, s36
	s_addc_u32 s37, s0, s37
	global_load_dwordx4 v[10:13], v78, s[36:37] offset:16 nt
	global_load_dwordx4 v[14:17], v78, s[36:37] nt
	global_load_dwordx4 v[2:5], v78, s[36:37] offset:2064 nt
	global_load_dwordx4 v[6:9], v78, s[36:37] offset:2048 nt

; __device__ __forceinline__ void rms_row_to_bf16(Frame& F, const f32x4 (&v)[4], bf16* orow, float* xinv_row) {
;     ...
;     for (int j = 0; j < 4; ++j) { s += (v[j].x * v[j].x + v[j].y * v[j].y) + (v[j].z * v[j].z + v[j].w * v[j].w); }
;     const float ms = wave_sum(s) * (1.f / D) + EPS, rstd = __builtin_amdgcn_rsqf(ms), rms = ms * rstd;
;     if (F.lane == 0) *xinv_row = rms;
; __device__ __forceinline__ void p0_prologue(Frame& F) {
;     ...
;     if (F.wave < P0_WW) {
;     const int gw = F.vcu * P0_WW + F.wave, NGW = F.G * P0_WW;
;     const int gt = gw * 64 + F.lane, NGT = NGW * 64;
;     for (int it = gt; it < 2048; it += NGT) {
;         const int pos = it >> 4, f = it & 15; double invf = 1.0;
;         for (int i = 0; i < f; ++i) invf *= 0.5623413251903491;
.LBB0_36:
	v_mul_f32_e32 v18, v15, v15
	v_mul_f32_e32 v19, v17, v17
	v_fmac_f32_e32 v18, v14, v14
	v_fmac_f32_e32 v19, v16, v16
	v_add_f32_e32 v18, v18, v19
	v_mul_f32_e32 v19, v11, v11
	v_mul_f32_e32 v20, v13, v13
	v_fmac_f32_e32 v19, v10, v10
	v_fmac_f32_e32 v20, v12, v12
	v_add_f32_e32 v19, v19, v20
	v_add_f32_e32 v18, v19, v18
	v_mul_f32_e32 v19, v7, v7
	v_mul_f32_e32 v20, v9, v9
	v_fmac_f32_e32 v19, v6, v6
	v_fmac_f32_e32 v20, v8, v8
	v_add_f32_e32 v19, v19, v20
	v_add_f32_e32 v18, v19, v18
	v_mul_f32_e32 v19, v3, v3
	v_mul_f32_e32 v20, v5, v5
	v_fmac_f32_e32 v19, v2, v2
	v_fmac_f32_e32 v20, v4, v4
	v_add_f32_e32 v19, v19, v20
	v_add_f32_e32 v18, v19, v18
	ds_bpermute_b32 v19, v72, v18
	s_ashr_i32 s7, s6, 31
	s_waitcnt lgkmcnt(0)
	v_add_f32_e32 v18, v18, v19
	ds_bpermute_b32 v19, v73, v18
	s_waitcnt lgkmcnt(0)
	v_add_f32_e32 v18, v18, v19
	ds_bpermute_b32 v19, v74, v18
	s_waitcnt lgkmcnt(0)
	v_add_f32_e32 v18, v18, v19
	ds_bpermute_b32 v19, v75, v18
	s_waitcnt lgkmcnt(0)
	v_add_f32_e32 v18, v18, v19
	ds_bpermute_b32 v19, v76, v18
	s_waitcnt lgkmcnt(0)
	v_add_f32_e32 v18, v18, v19
	ds_bpermute_b32 v19, v77, v18
	s_waitcnt lgkmcnt(0)
	v_add_f32_e32 v18, v18, v19
	v_fmamk_f32 v19, v18, 0x3a800000, v79
	v_rsq_f32_e32 v18, v19
	s_and_saveexec_b64 s[22:23], s[4:5]
	s_cbranch_execz .LBB0_17
	s_lshl_b64 s[24:25], s[6:7], 2
	s_add_u32 s24, s80, s24
	s_addc_u32 s25, s81, s25
	v_mul_f32_e32 v19, v19, v18
	global_store_dword v67, v19, s[24:25]
	s_branch .LBB0_17
.LBB0_38:
	s_mov_b64 s[4:5], -1
.LBB0_39:
	s_andn2_b64 vcc, exec, s[4:5]
	s_cbranch_vccnz .LBB0_167
	s_lshl_b32 s0, s43, 3
	s_or_b32 s69, s0, s87
	v_lshl_or_b32 v89, s69, 6, v1
	s_movk_i32 s0, 0x800
	s_lshl_b32 s36, s42, 9
	v_cmp_gt_i32_e32 vcc, s0, v89
	s_and_saveexec_b64 s[22:23], vcc
	s_cbranch_execz .LBB0_49
	v_and_b32_e32 v12, 15, v208
	s_mov_b32 s26, 0x3c1c381e
	s_mov_b32 s28, 0x6dc9c883
	s_mov_b32 s30, 0x54442d18
	v_cmp_ne_u32_e64 s[4:5], 0, v12
	s_mov_b64 s[24:25], 0
	s_mov_b32 s27, 0x3fe1feb3
	s_mov_b32 s29, 0x3fc45f30
	s_mov_b32 s31, 0xc01921fb
	s_movk_i32 s37, 0x7ff
	v_mov_b32_e32 v2, v89

; __device__ __forceinline__ void p0_prologue(Frame& F) {
;     ...
;     for (int it = gt; it < 128 * 1024; it += NGT) {
;         const int jb = __builtin_amdgcn_readfirstlane(it >> 10), n = it & 1023, g = jb >> 5, jj0 = (jb & 31) * 4;
;         const float* wp = F.wpool + ((size_t)g * 128 + jj0) * 128; const float* ps = F.pscale + g * 128; const float* wo = F.wout + (size_t)(512 + g * 128) * 1024 + n;
.LBB0_49:
	s_or_b64 exec, exec, s[22:23]
	s_mov_b32 s0, 0x20000
	v_cmp_gt_i32_e32 vcc, s0, v89
	s_and_saveexec_b64 s[4:5], vcc
	s_cbranch_execz .LBB0_54
	s_add_u32 s30, s8, 0x200000
	s_addc_u32 s31, s9, 0
	s_lshl_b32 s0, s43, 9
	s_and_b32 s1, s88, 0x3c0
	s_add_i32 s0, s0, s1
	v_bitop3_b16 v93, s0, v208, 63 bitop3:0xf8
	s_mov_b64 s[6:7], 0
	v_mov_b32_e32 v85, 0
	s_mov_b64 s[22:23], 0x20000
	s_mov_b32 s34, 0x1ffff

; #define LAS __attribute__((address_space(3)))
; #define LDS_WAIT() asm volatile("s_waitcnt lgkmcnt(0)" ::: "memory")
; __device__ __forceinline__ unsigned pk2(float lo, float hi) { const f32x2_pk v = {lo, hi}; return __builtin_bit_cast(unsigned, __builtin_convertvector(v, bf16x2_pk)); }
; __device__ __forceinline__ void titem_store(int tN, bf16* tWT, int tldt, const float* tks, int tmode, int tr, LAS float* scr, int lane, const float (&v)[32]) {
;     const int nblk = tN / 32, kb = tr / nblk, nb = tr % nblk, k0 = 64 * kb, n0 = 32 * nb;
; #pragma unroll
;     for (int i = 0; i < 32; ++i) { const int kk = 2 * i + (lane >> 5); float x = v[i]; if (tks) x *= tks[k0 + kk]; scr[kk * 33 + (lane & 31)] = x; }
;     LDS_WAIT(); asm volatile("" ::: "memory");
;     const int c = lane & 7;
; #pragma unroll
;     for (int j = 0; j < 4; ++j) { const int n = (lane >> 3) + 8 * j; const LAS float* sp = scr + (8 * c) * 33 + n;
;         v4u o; o.x = pk2(sp[0 * 33], sp[1 * 33]); o.y = pk2(sp[2 * 33], sp[3 * 33]); o.z = pk2(sp[4 * 33], sp[5 * 33]); o.w = pk2(sp[6 * 33], sp[7 * 33]);
; __device__ __forceinline__ void p0_prologue(Frame& F) {
;     ...
;     for (int it = gw; it < NITEMS; it += 2 * NGW) {
;         const int it2 = it + NGW; const bool two = it2 < NITEMS;
;         P0_DECODE(ta, it) P0_DECODE(tb, two ? it2 : it)
;         float va[32], vb[32];
;         titem_load(taW, taN, tar, F.lane, va); titem_load(tbW, tbN, tbr, F.lane, vb);
;         titem_store(taN, taWT, taldt, taks, tamode, tar, scr, F.lane, va); if (two) titem_store(tbN, tbWT, tbldt, tbks, tbmode, tbr, scr, F.lane, vb);
.LBB0_54:
	s_or_b64 exec, exec, s[4:5]
	s_cmpk_gt_i32 s69, 0x137f
	s_cbranch_scc1 .LBB0_167
	v_lshrrev_b32_e32 v2, 5, v1
	s_movk_i32 s1, 0x84
	v_mov_b32_e32 v3, 0x210
	v_mad_u32_u24 v11, v2, s1, v3
	v_mov_b32_e32 v3, 0x420
	v_mad_u32_u24 v12, v2, s1, v3
	v_mov_b32_e32 v3, 0x630
	v_mad_u32_u24 v13, v2, s1, v3
	v_mov_b32_e32 v3, 0x840
	v_mad_u32_u24 v14, v2, s1, v3
	v_mov_b32_e32 v3, 0xa50
	v_mad_u32_u24 v15, v2, s1, v3
	v_mov_b32_e32 v3, 0xc60
	v_mad_u32_u24 v16, v2, s1, v3
	v_mov_b32_e32 v3, 0xe70
	v_mad_u32_u24 v17, v2, s1, v3
	v_mov_b32_e32 v3, 0x1080
	v_mad_u32_u24 v18, v2, s1, v3
	v_mov_b32_e32 v3, 0x1290
	v_mad_u32_u24 v19, v2, s1, v3
	v_mov_b32_e32 v3, 0x14a0
	v_mad_u32_u24 v20, v2, s1, v3
	v_lshlrev_b32_e32 v3, 3, v208
	s_lshl_b32 s0, s87, 14
	v_lshrrev_b32_e32 v44, 3, v1
	v_and_b32_e32 v8, 56, v3
	s_addk_i32 s0, 0x100
	v_mul_u32_u24_e32 v3, 0x84, v8
	v_lshlrev_b32_e32 v7, 2, v44
	v_add3_u32 v45, s0, v3, v7
	v_lshrrev_b32_e32 v3, 2, v1
	v_or_b32_e32 v47, 8, v44
	v_bfe_u32 v6, v1, 3, 2
	v_and_b32_e32 v3, 8, v3
	v_lshlrev_b32_e32 v7, 1, v47
	v_or_b32_e32 v50, 24, v44
	v_and_b32_e32 v4, 31, v208
	v_or_b32_e32 v46, v3, v6
	v_and_or_b32 v48, v7, 24, v6
	v_lshlrev_b32_e32 v6, 1, v50
	v_mov_b32_e32 v5, 0
	v_lshl_add_u32 v9, v4, 2, s0
	v_mul_u32_u24_e32 v10, 0x84, v2
	v_and_b32_e32 v6, 24, v6
	s_lshl_b32 s89, s42, 3
	s_lshl_b32 s90, s42, 4
	v_or_b32_e32 v49, 16, v44
	v_or3_b32 v51, v3, v44, 4
	v_or3_b32 v52, v6, v44, 4
	v_mov_b32_e32 v3, v5
	v_lshlrev_b32_e32 v6, 2, v4
	v_mov_b32_e32 v7, v5
	v_lshlrev_b32_e32 v4, 1, v8
	v_add_u32_e32 v53, v9, v10
	v_add_u32_e32 v54, v9, v11
	v_add_u32_e32 v55, v9, v12
	v_add_u32_e32 v56, v9, v13
	v_add_u32_e32 v57, v9, v14
	v_add_u32_e32 v58, v9, v15
	v_add_u32_e32 v59, v9, v16
	v_add_u32_e32 v60, v9, v17
	v_add_u32_e32 v61, v9, v18
	v_add_u32_e32 v62, v9, v19
	v_add_u32_e32 v63, v9, v20
	s_branch .LBB0_58
